# stick-breaking non-diagonal bodies: each step's 1/(1+e) gets its own spare VGPR instead of the shared temp, 96 v_mov copies removed (pure renaming; s_nop 0 kept between a trans op and its reader)
# speedup vs baseline: 1.0050x; 1.0050x over previous
; DI unsigned pk2(float lo, float hi) { f32x2 v = {lo, hi}; bf2_t r = __builtin_convertvector(v, bf2_t); return __builtin_bit_cast(unsigned, r); }
; DI void xhalf(float x, float& lo, float& hi) { const u32x2p r = __builtin_amdgcn_permlane32_swap(__float_as_uint(x), __float_as_uint(x), false, false); lo = __uint_as_float(r.x); hi = __uint_as_float(r.y); }
; #define MFMA32(a, b, c) __builtin_amdgcn_mfma_f32_32x32x16_bf16((a), (b), (c), 0, 0, 0)
; DI void sb_block2(const Params& p, LAS unsigned char* lds, int bh, int qb2, int tid) {
;     ...
;                     for (int g = 0; g < 2; ++g) {
;                         if (g == 0 ? act0 : act1) {
;                             const f32x16 z = zz[g];
;                             const bool diag = (kb == q0[g]);
;                             f32x16 a;
;                             float tot = 1.f;
; #pragma unroll
;                             for (int i = 15; i >= 0; --i) {
;                                 const float w = __builtin_amdgcn_exp2f(fminf(z[i], 86.f));
;                                 float be = __builtin_amdgcn_rcpf(1.f + w);
;                                 float om = w * be;
;                                 if (diag) { const bool valid = (16 * h + i < r); be = valid ? be : 0.f; om = valid ? om : 1.f; }
;                                 a[i] = be * tot;
;                                 tot *= om;
;                             }
;                             float tlo, thi; xhalf(tot, tlo, thi);
;                             const float bs = carry[g] * (h == 0 ? thi : 1.f);
;                             carry[g] *= tlo * thi;
; #pragma unroll
;                             for (int i = 0; i < 16; ++i) a[i] *= bs;
;                             bf16x8 pf[2];
; #pragma unroll
;                             for (int s2 = 0; s2 < 2; ++s2) {
;                                 u32x4 w; w.x = pk2(a[8 * s2 + 0], a[8 * s2 + 1]); w.y = pk2(a[8 * s2 + 2], a[8 * s2 + 3]); w.z = pk2(a[8 * s2 + 4], a[8 * s2 + 5]); w.w = pk2(a[8 * s2 + 6], a[8 * s2 + 7]);
;                                 pf[s2] = __builtin_bit_cast(bf16x8, w);
;                             }
; #pragma unroll
;                             for (int s2 = 0; s2 < 2; ++s2) { o0[g] = MFMA32(vf[s2], pf[s2], o0[g]); o1[g] = MFMA32(vf[2 + s2], pf[s2], o1[g]); }
.Lsb_lean_0:
	v_min_f32_e32 v17, 0x42ac0000, v33
	v_exp_f32_e32 v17, v17
	v_min_f32_e32 v32, 0x42ac0000, v32
	v_exp_f32_e32 v32, v32
	v_add_f32_e32 v33, 1.0, v17
	v_rcp_f32_e32 v33, v33
	v_add_f32_e32 v50, 1.0, v32
	v_rcp_f32_e32 v50, v50
	v_min_f32_e32 v31, 0x42ac0000, v31
	v_exp_f32_e32 v31, v31
	v_mul_f32_e32 v17, v17, v33
	v_mul_f32_e32 v32, v32, v50
	v_add_f32_e32 v197, 1.0, v31
	v_rcp_f32_e32 v197, v197
	v_min_f32_e32 v30, 0x42ac0000, v30
	v_exp_f32_e32 v30, v30
	v_mov_b32_e32 v52, v32
	v_mul_f32_e32 v32, v50, v17
	v_mul_f32_e32 v31, v31, v197
	v_add_f32_e32 v198, 1.0, v30
	v_rcp_f32_e32 v198, v198
	v_min_f32_e32 v29, 0x42ac0000, v29
	v_exp_f32_e32 v29, v29
	v_mul_f32_e32 v17, v17, v52
	v_mul_f32_e32 v82, v197, v17
	v_mul_f32_e32 v17, v31, v17
	v_mul_f32_e32 v30, v30, v198
	v_add_f32_e32 v199, 1.0, v29
	v_rcp_f32_e32 v199, v199
	v_min_f32_e32 v28, 0x42ac0000, v28
	v_exp_f32_e32 v28, v28
	v_mul_f32_e32 v31, v198, v17
	v_mul_f32_e32 v17, v30, v17
	v_mul_f32_e32 v29, v29, v199
	v_add_f32_e32 v200, 1.0, v28
	v_rcp_f32_e32 v200, v200
	v_min_f32_e32 v27, 0x42ac0000, v27
	v_exp_f32_e32 v27, v27
	v_mul_f32_e32 v30, v199, v17
	v_mul_f32_e32 v17, v29, v17
	v_mul_f32_e32 v28, v28, v200
	v_add_f32_e32 v201, 1.0, v27
	v_rcp_f32_e32 v201, v201
	v_min_f32_e32 v26, 0x42ac0000, v26
	v_exp_f32_e32 v26, v26
	v_min_f32_e32 v25, 0x42ac0000, v25
	v_mul_f32_e32 v27, v27, v201
	v_exp_f32_e32 v25, v25
	v_mul_f32_e32 v29, v200, v17
	v_mul_f32_e32 v17, v28, v17
	v_add_f32_e32 v50, 1.0, v26
	v_rcp_f32_e32 v50, v50
	v_mul_f32_e32 v28, v201, v17
	v_mul_f32_e32 v17, v27, v17
	v_add_f32_e32 v27, 1.0, v25
	v_rcp_f32_e32 v27, v27
	v_min_f32_e32 v24, 0x42ac0000, v24
	v_exp_f32_e32 v24, v24
	v_mul_f32_e32 v26, v26, v50
	v_mul_f32_e32 v25, v25, v27
	v_add_f32_e32 v202, 1.0, v24
	v_rcp_f32_e32 v202, v202
	v_min_f32_e32 v23, 0x42ac0000, v23
	v_exp_f32_e32 v23, v23
	v_mul_f32_e32 v26, v26, v17
	v_mul_f32_e32 v27, v27, v26
	v_mul_f32_e32 v25, v25, v26
	v_mul_f32_e32 v24, v24, v202
	v_add_f32_e32 v203, 1.0, v23
	v_rcp_f32_e32 v203, v203
	v_min_f32_e32 v22, 0x42ac0000, v22
	v_exp_f32_e32 v22, v22
	v_mul_f32_e32 v26, v202, v25
	v_mul_f32_e32 v24, v24, v25
	v_mul_f32_e32 v23, v23, v203
	v_add_f32_e32 v204, 1.0, v22
	v_rcp_f32_e32 v204, v204
	v_min_f32_e32 v21, 0x42ac0000, v21
	v_exp_f32_e32 v21, v21
	v_mul_f32_e32 v25, v203, v24
	v_mul_f32_e32 v23, v23, v24
	v_mul_f32_e32 v22, v22, v204
	v_add_f32_e32 v205, 1.0, v21
	v_rcp_f32_e32 v205, v205
	v_min_f32_e32 v20, 0x42ac0000, v20
	v_exp_f32_e32 v20, v20
	v_mul_f32_e32 v24, v204, v23
	v_mul_f32_e32 v22, v22, v23
	v_mul_f32_e32 v21, v21, v205
	v_add_f32_e32 v206, 1.0, v20
	v_rcp_f32_e32 v206, v206
	v_min_f32_e32 v19, 0x42ac0000, v19
	v_exp_f32_e32 v19, v19
	v_mul_f32_e32 v23, v205, v22
	v_mul_f32_e32 v21, v21, v22
	v_mul_f32_e32 v20, v20, v206
	v_add_f32_e32 v207, 1.0, v19
	v_rcp_f32_e32 v207, v207
	v_min_f32_e32 v18, 0x42ac0000, v18
	v_exp_f32_e32 v18, v18
	v_mul_f32_e32 v52, v206, v21
	v_mul_f32_e32 v20, v20, v21
	v_mul_f32_e32 v19, v19, v207
	v_add_f32_e32 v51, 1.0, v18
	v_rcp_f32_e32 v51, v51
	v_mul_f32_e32 v19, v19, v20
	v_mul_f32_e32 v18, v18, v51
	v_mul_f32_e32 v83, v18, v19
	v_mul_f32_e32 v21, v207, v20
	v_mov_b32_e32 v84, v83
	v_mov_b32_e32 v20, v51
	s_nop 0
	v_permlane32_swap_b32_e32 v83, v84
	v_mul_f32_e32 v20, v20, v19
	v_cndmask_b32_e64 v22, 1.0, v84, s[10:11]
	v_mul_f32_e32 v18, v20, v22
	v_mul_f32_e32 v19, v21, v22
	v_mul_f32_e32 v20, v52, v22
	v_mul_f32_e32 v21, v23, v22
	v_mul_f32_e32 v23, v24, v22
	v_mul_f32_e32 v24, v25, v22
	v_mul_f32_e32 v25, v26, v22
	v_mul_f32_e32 v26, v27, v22
	v_cvt_pk_bf16_f32 v18, v18, v19
	v_cvt_pk_bf16_f32 v19, v20, v21
	v_cvt_pk_bf16_f32 v20, v23, v24
	v_cvt_pk_bf16_f32 v21, v25, v26
	v_mov_b32_e32 v23, v50
	s_nop 0
	v_mfma_f32_32x32x16_bf16 v[66:81], v[46:49], v[18:21], 0
	v_mul_f32_e32 v17, v23, v17
	v_mul_f32_e32 v17, v17, v22
	v_mul_f32_e32 v24, v28, v22
	v_mul_f32_e32 v25, v29, v22
	v_mul_f32_e32 v26, v30, v22
	v_mul_f32_e32 v190, v83, v84

; DI unsigned pk2(float lo, float hi) { f32x2 v = {lo, hi}; bf2_t r = __builtin_convertvector(v, bf2_t); return __builtin_bit_cast(unsigned, r); }
; DI void xhalf(float x, float& lo, float& hi) { const u32x2p r = __builtin_amdgcn_permlane32_swap(__float_as_uint(x), __float_as_uint(x), false, false); lo = __uint_as_float(r.x); hi = __uint_as_float(r.y); }
; #define MFMA32(a, b, c) __builtin_amdgcn_mfma_f32_32x32x16_bf16((a), (b), (c), 0, 0, 0)
; DI void sb_block2(const Params& p, LAS unsigned char* lds, int bh, int qb2, int tid) {
;     ...
;                     for (int g = 0; g < 2; ++g) {
;                         if (g == 0 ? act0 : act1) {
;                             const f32x16 z = zz[g];
;                             const bool diag = (kb == q0[g]);
;                             f32x16 a;
;                             float tot = 1.f;
; #pragma unroll
;                             for (int i = 15; i >= 0; --i) {
;                                 const float w = __builtin_amdgcn_exp2f(fminf(z[i], 86.f));
;                                 float be = __builtin_amdgcn_rcpf(1.f + w);
;                                 float om = w * be;
;                                 if (diag) { const bool valid = (16 * h + i < r); be = valid ? be : 0.f; om = valid ? om : 1.f; }
;                                 a[i] = be * tot;
;                                 tot *= om;
;                             }
;                             float tlo, thi; xhalf(tot, tlo, thi);
;                             const float bs = carry[g] * (h == 0 ? thi : 1.f);
;                             carry[g] *= tlo * thi;
; #pragma unroll
;                             for (int i = 0; i < 16; ++i) a[i] *= bs;
;                             bf16x8 pf[2];
; #pragma unroll
;                             for (int s2 = 0; s2 < 2; ++s2) {
;                                 u32x4 w; w.x = pk2(a[8 * s2 + 0], a[8 * s2 + 1]); w.y = pk2(a[8 * s2 + 2], a[8 * s2 + 3]); w.z = pk2(a[8 * s2 + 4], a[8 * s2 + 5]); w.w = pk2(a[8 * s2 + 6], a[8 * s2 + 7]);
;                                 pf[s2] = __builtin_bit_cast(bf16x8, w);
;                             }
; #pragma unroll
;                             for (int s2 = 0; s2 < 2; ++s2) { o0[g] = MFMA32(vf[s2], pf[s2], o0[g]); o1[g] = MFMA32(vf[2 + s2], pf[s2], o1[g]); }
.Lsb_lean_1:
	v_min_f32_e32 v15, 0x42ac0000, v15
	v_exp_f32_e32 v15, v15
	v_min_f32_e32 v14, 0x42ac0000, v14
	v_exp_f32_e32 v14, v14
	v_add_f32_e32 v17, 1.0, v15
	v_rcp_f32_e32 v17, v17
	v_add_f32_e32 v18, 1.0, v14
	v_rcp_f32_e32 v18, v18
	v_min_f32_e32 v13, 0x42ac0000, v13
	v_exp_f32_e32 v13, v13
	v_mul_f32_e32 v197, v15, v17
	v_mov_b32_e32 v15, v17
	v_mul_f32_e32 v14, v14, v18
	v_add_f32_e32 v198, 1.0, v13
	v_rcp_f32_e32 v198, v198
	v_min_f32_e32 v12, 0x42ac0000, v12
	v_exp_f32_e32 v12, v12
	v_mov_b32_e32 v20, v14
	v_mul_f32_e32 v14, v18, v197
	v_mul_f32_e32 v13, v13, v198
	v_add_f32_e32 v199, 1.0, v12
	v_rcp_f32_e32 v199, v199
	v_min_f32_e32 v11, 0x42ac0000, v11
	v_exp_f32_e32 v11, v11
	v_mul_f32_e32 v17, v197, v20
	v_mul_f32_e32 v18, v198, v17
	v_mul_f32_e32 v13, v13, v17
	v_mul_f32_e32 v12, v12, v199
	v_add_f32_e32 v200, 1.0, v11
	v_rcp_f32_e32 v200, v200
	v_min_f32_e32 v10, 0x42ac0000, v10
	v_exp_f32_e32 v10, v10
	v_mul_f32_e32 v17, v199, v13
	v_mul_f32_e32 v12, v12, v13
	v_mul_f32_e32 v11, v11, v200
	v_add_f32_e32 v201, 1.0, v10
	v_rcp_f32_e32 v201, v201
	v_min_f32_e32 v9, 0x42ac0000, v9
	v_exp_f32_e32 v9, v9
	v_mul_f32_e32 v13, v200, v12
	v_mul_f32_e32 v11, v11, v12
	v_mul_f32_e32 v10, v10, v201
	v_add_f32_e32 v202, 1.0, v9
	v_rcp_f32_e32 v202, v202
	v_min_f32_e32 v8, 0x42ac0000, v8
	v_exp_f32_e32 v8, v8
	v_min_f32_e32 v7, 0x42ac0000, v7
	v_exp_f32_e32 v7, v7
	v_mul_f32_e32 v12, v201, v11
	v_mul_f32_e32 v10, v10, v11
	v_mul_f32_e32 v9, v9, v202
	v_add_f32_e32 v19, 1.0, v8
	v_rcp_f32_e32 v19, v19
	v_mul_f32_e32 v11, v202, v10
	v_mul_f32_e32 v9, v9, v10
	v_add_f32_e32 v10, 1.0, v7
	v_rcp_f32_e32 v10, v10
	v_min_f32_e32 v6, 0x42ac0000, v6
	v_exp_f32_e32 v6, v6
	v_mul_f32_e32 v8, v8, v19
	v_mul_f32_e32 v7, v7, v10
	v_add_f32_e32 v203, 1.0, v6
	v_rcp_f32_e32 v203, v203
	v_min_f32_e32 v5, 0x42ac0000, v5
	v_exp_f32_e32 v5, v5
	v_mul_f32_e32 v8, v8, v9
	v_mul_f32_e32 v10, v10, v8
	v_mul_f32_e32 v7, v7, v8
	v_mul_f32_e32 v6, v6, v203
	v_add_f32_e32 v204, 1.0, v5
	v_rcp_f32_e32 v204, v204
	v_min_f32_e32 v4, 0x42ac0000, v4
	v_exp_f32_e32 v4, v4
	v_mul_f32_e32 v8, v203, v7
	v_mul_f32_e32 v6, v6, v7
	v_mul_f32_e32 v5, v5, v204
	v_add_f32_e32 v205, 1.0, v4
	v_rcp_f32_e32 v205, v205
	v_min_f32_e32 v3, 0x42ac0000, v3
	v_exp_f32_e32 v3, v3
	v_mul_f32_e32 v7, v204, v6
	v_mul_f32_e32 v5, v5, v6
	v_mul_f32_e32 v4, v4, v205
	v_add_f32_e32 v206, 1.0, v3
	v_rcp_f32_e32 v206, v206
	v_min_f32_e32 v2, 0x42ac0000, v2
	v_exp_f32_e32 v2, v2
	v_mul_f32_e32 v6, v205, v5
	v_mul_f32_e32 v4, v4, v5
	v_mul_f32_e32 v3, v3, v206
	v_add_f32_e32 v207, 1.0, v2
	v_rcp_f32_e32 v207, v207
	v_min_f32_e32 v1, 0x42ac0000, v1
	v_exp_f32_e32 v1, v1
	v_mul_f32_e32 v5, v206, v4
	v_mul_f32_e32 v3, v3, v4
	v_mul_f32_e32 v2, v2, v207
	v_add_f32_e32 v208, 1.0, v1
	v_rcp_f32_e32 v208, v208
	v_min_f32_e32 v0, 0x42ac0000, v0
	v_exp_f32_e32 v0, v0
	v_mul_f32_e32 v21, v207, v3
	v_mul_f32_e32 v2, v2, v3
	v_mul_f32_e32 v1, v1, v208
	v_add_f32_e32 v209, 1.0, v0
	v_rcp_f32_e32 v209, v209
	v_mul_f32_e32 v3, v208, v2
	v_mul_f32_e32 v0, v0, v209
	v_mul_f32_e32 v1, v1, v2
	v_mul_f32_e32 v20, v0, v1
	v_mov_b32_e32 v22, v20
	s_nop 1
	s_nop 0
	v_permlane32_swap_b32_e32 v20, v22
	v_mul_f32_e32 v2, v209, v1
	v_cndmask_b32_e64 v4, 1.0, v22, s[10:11]
	v_mul_f32_e32 v0, v2, v4
	v_mul_f32_e32 v1, v3, v4
	v_mul_f32_e32 v2, v21, v4
	v_mul_f32_e32 v3, v5, v4
	v_mul_f32_e32 v5, v6, v4
	v_mul_f32_e32 v6, v7, v4
	v_mul_f32_e32 v7, v8, v4
	v_mul_f32_e32 v8, v10, v4
	v_cvt_pk_bf16_f32 v0, v0, v1
	v_cvt_pk_bf16_f32 v1, v2, v3
	v_cvt_pk_bf16_f32 v2, v5, v6
	v_cvt_pk_bf16_f32 v3, v7, v8
	v_mov_b32_e32 v5, v19
	s_nop 0
	v_mfma_f32_32x32x16_bf16 v[98:113], v[46:49], v[0:3], 0
	v_mul_f32_e32 v5, v5, v9
	v_mul_f32_e32 v6, v5, v4
	v_mul_f32_e32 v7, v11, v4
	v_mul_f32_e32 v8, v12, v4
	v_mul_f32_e32 v9, v13, v4
	v_mul_f32_e32 v191, v20, v22

; DI unsigned pk2(float lo, float hi) { f32x2 v = {lo, hi}; bf2_t r = __builtin_convertvector(v, bf2_t); return __builtin_bit_cast(unsigned, r); }
; DI void xhalf(float x, float& lo, float& hi) { const u32x2p r = __builtin_amdgcn_permlane32_swap(__float_as_uint(x), __float_as_uint(x), false, false); lo = __uint_as_float(r.x); hi = __uint_as_float(r.y); }
; #define MFMA32(a, b, c) __builtin_amdgcn_mfma_f32_32x32x16_bf16((a), (b), (c), 0, 0, 0)
; DI void sb_block2(const Params& p, LAS unsigned char* lds, int bh, int qb2, int tid) {
;     ...
;                     for (int g = 0; g < 2; ++g) {
;                         if (g == 0 ? act0 : act1) {
;                             const f32x16 z = zz[g];
;                             const bool diag = (kb == q0[g]);
;                             f32x16 a;
;                             float tot = 1.f;
; #pragma unroll
;                             for (int i = 15; i >= 0; --i) {
;                                 const float w = __builtin_amdgcn_exp2f(fminf(z[i], 86.f));
;                                 float be = __builtin_amdgcn_rcpf(1.f + w);
;                                 float om = w * be;
;                                 if (diag) { const bool valid = (16 * h + i < r); be = valid ? be : 0.f; om = valid ? om : 1.f; }
;                                 a[i] = be * tot;
;                                 tot *= om;
;                             }
;                             float tlo, thi; xhalf(tot, tlo, thi);
;                             const float bs = carry[g] * (h == 0 ? thi : 1.f);
;                             carry[g] *= tlo * thi;
; #pragma unroll
;                             for (int i = 0; i < 16; ++i) a[i] *= bs;
;                             bf16x8 pf[2];
; #pragma unroll
;                             for (int s2 = 0; s2 < 2; ++s2) {
;                                 u32x4 w; w.x = pk2(a[8 * s2 + 0], a[8 * s2 + 1]); w.y = pk2(a[8 * s2 + 2], a[8 * s2 + 3]); w.z = pk2(a[8 * s2 + 4], a[8 * s2 + 5]); w.w = pk2(a[8 * s2 + 6], a[8 * s2 + 7]);
;                                 pf[s2] = __builtin_bit_cast(bf16x8, w);
;                             }
; #pragma unroll
;                             for (int s2 = 0; s2 < 2; ++s2) { o0[g] = MFMA32(vf[s2], pf[s2], o0[g]); o1[g] = MFMA32(vf[2 + s2], pf[s2], o1[g]); }
.Lsb_lean_2:
	v_min_f32_e32 v197, 0x42ac0000, v49
	v_exp_f32_e32 v197, v197
	v_min_f32_e32 v1, 0x42ac0000, v48
	v_exp_f32_e32 v2, v1
	v_add_f32_e32 v1, 1.0, v197
	v_rcp_f32_e32 v1, v1
	v_add_f32_e32 v3, 1.0, v2
	v_rcp_f32_e32 v3, v3
	v_mul_f32_e32 v197, v197, v1
	v_mul_f32_e32 v198, v2, v3
	v_min_f32_e32 v2, 0x42ac0000, v47
	v_exp_f32_e32 v2, v2
	s_nop 0
	v_add_f32_e32 v5, 1.0, v2
	v_mul_f32_e32 v0, v3, v197
	v_mul_f32_e32 v3, v197, v198
	v_rcp_f32_e32 v5, v5
	v_min_f32_e32 v4, 0x42ac0000, v46
	v_exp_f32_e32 v4, v4
	v_mul_f32_e32 v2, v2, v5
	v_add_f32_e32 v199, 1.0, v4
	v_rcp_f32_e32 v199, v199
	v_mul_f32_e32 v7, v5, v3
	v_mul_f32_e32 v2, v2, v3
	v_mul_f32_e32 v3, v4, v199
	v_min_f32_e32 v4, 0x42ac0000, v45
	v_exp_f32_e32 v4, v4
	s_nop 0
	v_add_f32_e32 v200, 1.0, v4
	v_rcp_f32_e32 v200, v200
	v_mul_f32_e32 v8, v199, v2
	v_mul_f32_e32 v2, v3, v2
	v_mul_f32_e32 v3, v4, v200
	v_min_f32_e32 v4, 0x42ac0000, v44
	v_exp_f32_e32 v4, v4
	s_nop 0
	v_add_f32_e32 v201, 1.0, v4
	v_rcp_f32_e32 v201, v201
	v_mul_f32_e32 v9, v200, v2
	v_mul_f32_e32 v2, v3, v2
	v_mul_f32_e32 v3, v4, v201
	v_min_f32_e32 v4, 0x42ac0000, v43
	v_exp_f32_e32 v4, v4
	s_nop 0
	v_add_f32_e32 v202, 1.0, v4
	v_mul_f32_e32 v10, v201, v2
	v_rcp_f32_e32 v202, v202
	v_min_f32_e32 v5, 0x42ac0000, v42
	v_exp_f32_e32 v5, v5
	v_mul_f32_e32 v2, v3, v2
	v_mul_f32_e32 v3, v4, v202
	v_add_f32_e32 v6, 1.0, v5
	v_rcp_f32_e32 v11, v6
	v_min_f32_e32 v6, 0x42ac0000, v41
	v_exp_f32_e32 v6, v6
	v_mul_f32_e32 v12, v202, v2
	v_mul_f32_e32 v13, v3, v2
	v_mul_f32_e32 v2, v5, v11
	v_add_f32_e32 v3, 1.0, v6
	v_rcp_f32_e32 v3, v3
	v_min_f32_e32 v5, 0x42ac0000, v40
	v_exp_f32_e32 v5, v5
	v_mul_f32_e32 v4, v6, v3
	v_add_f32_e32 v6, 1.0, v5
	v_rcp_f32_e32 v6, v6
	v_mul_f32_e32 v2, v2, v13
	v_mul_f32_e32 v3, v3, v2
	v_mul_f32_e32 v2, v4, v2
	v_mul_f32_e32 v4, v5, v6
	v_min_f32_e32 v5, 0x42ac0000, v39
	v_exp_f32_e32 v5, v5
	s_nop 0
	v_add_f32_e32 v203, 1.0, v5
	v_rcp_f32_e32 v203, v203
	v_mul_f32_e32 v15, v6, v2
	v_mul_f32_e32 v2, v4, v2
	v_mul_f32_e32 v4, v5, v203
	v_min_f32_e32 v5, 0x42ac0000, v38
	v_exp_f32_e32 v5, v5
	s_nop 0
	v_add_f32_e32 v204, 1.0, v5
	v_rcp_f32_e32 v204, v204
	v_mul_f32_e32 v17, v203, v2
	v_mul_f32_e32 v2, v4, v2
	v_mul_f32_e32 v4, v5, v204
	v_min_f32_e32 v5, 0x42ac0000, v37
	v_exp_f32_e32 v5, v5
	s_nop 0
	v_add_f32_e32 v205, 1.0, v5
	v_rcp_f32_e32 v205, v205
	v_mul_f32_e32 v18, v204, v2
	v_mul_f32_e32 v2, v4, v2
	v_mul_f32_e32 v4, v5, v205
	v_min_f32_e32 v5, 0x42ac0000, v36
	v_exp_f32_e32 v5, v5
	s_nop 0
	v_add_f32_e32 v206, 1.0, v5
	v_rcp_f32_e32 v206, v206
	v_mul_f32_e32 v19, v205, v2
	v_mul_f32_e32 v2, v4, v2
	v_mul_f32_e32 v4, v5, v206
	v_min_f32_e32 v5, 0x42ac0000, v35
	v_exp_f32_e32 v5, v5
	s_nop 0
	v_add_f32_e32 v207, 1.0, v5
	v_rcp_f32_e32 v207, v207
	v_mul_f32_e32 v20, v206, v2
	v_mul_f32_e32 v2, v4, v2
	v_mul_f32_e32 v4, v5, v207
	v_min_f32_e32 v5, 0x42ac0000, v34
	v_exp_f32_e32 v5, v5
	s_nop 0
	v_add_f32_e32 v208, 1.0, v5
	v_rcp_f32_e32 v208, v208
	v_mul_f32_e32 v21, v207, v2
	v_mul_f32_e32 v2, v4, v2
	v_mul_f32_e32 v4, v5, v208
	v_mul_f32_e32 v14, v4, v2
	v_mov_b32_e32 v22, v14
	s_nop 1
	s_nop 0
	v_permlane32_swap_b32_e32 v14, v22
	v_mul_f32_e32 v5, v208, v2
	v_cndmask_b32_e64 v2, 1.0, v22, s[10:11]
	v_mul_f32_e32 v6, v191, v2
	v_mul_f32_e32 v2, v5, v6
	v_mul_f32_e32 v4, v21, v6
	v_mul_f32_e32 v5, v20, v6
	v_mul_f32_e32 v19, v19, v6
	v_mul_f32_e32 v18, v18, v6
	v_mul_f32_e32 v17, v17, v6
	v_mul_f32_e32 v15, v15, v6
	v_mul_f32_e32 v20, v3, v6
	v_cvt_pk_bf16_f32 v2, v2, v4
	v_cvt_pk_bf16_f32 v3, v5, v19
	v_cvt_pk_bf16_f32 v4, v18, v17
	v_cvt_pk_bf16_f32 v5, v15, v20
	v_cndmask_b32_e64 v15, 0, v11, s[28:29]
	s_waitcnt lgkmcnt(0)
	v_mfma_f32_32x32x16_bf16 v[98:113], v[158:161], v[2:5], v[98:113]
	v_mul_f32_e32 v11, v11, v13
	v_mul_f32_e32 v11, v11, v6
	v_mul_f32_e32 v12, v12, v6
	v_mul_f32_e32 v10, v10, v6
	v_mul_f32_e32 v9, v9, v6
	v_mfma_f32_32x32x16_bf16 v[82:97], v[154:157], v[2:5], v[82:97]
	v_mul_f32_e32 v2, v8, v6
	v_mul_f32_e32 v3, v7, v6
	v_mul_f32_e64 v4, v0, v6
	v_mul_f32_e64 v5, v1, v6
	v_cvt_pk_bf16_f32 v0, v11, v12
	v_cvt_pk_bf16_f32 v1, v10, v9
	v_cvt_pk_bf16_f32 v2, v2, v3
	v_cvt_pk_bf16_f32 v3, v4, v5
	v_mul_f32_e32 v4, v14, v22
	v_mul_f32_e32 v191, v191, v4
	v_mfma_f32_32x32x16_bf16 v[98:113], v[150:153], v[0:3], v[98:113]

; DI unsigned pk2(float lo, float hi) { f32x2 v = {lo, hi}; bf2_t r = __builtin_convertvector(v, bf2_t); return __builtin_bit_cast(unsigned, r); }
; DI void xhalf(float x, float& lo, float& hi) { const u32x2p r = __builtin_amdgcn_permlane32_swap(__float_as_uint(x), __float_as_uint(x), false, false); lo = __uint_as_float(r.x); hi = __uint_as_float(r.y); }
; #define MFMA32(a, b, c) __builtin_amdgcn_mfma_f32_32x32x16_bf16((a), (b), (c), 0, 0, 0)
; DI void sb_block2(const Params& p, LAS unsigned char* lds, int bh, int qb2, int tid) {
;     ...
;                     for (int g = 0; g < 2; ++g) {
;                         if (g == 0 ? act0 : act1) {
;                             const f32x16 z = zz[g];
;                             const bool diag = (kb == q0[g]);
;                             f32x16 a;
;                             float tot = 1.f;
; #pragma unroll
;                             for (int i = 15; i >= 0; --i) {
;                                 const float w = __builtin_amdgcn_exp2f(fminf(z[i], 86.f));
;                                 float be = __builtin_amdgcn_rcpf(1.f + w);
;                                 float om = w * be;
;                                 if (diag) { const bool valid = (16 * h + i < r); be = valid ? be : 0.f; om = valid ? om : 1.f; }
;                                 a[i] = be * tot;
;                                 tot *= om;
;                             }
;                             float tlo, thi; xhalf(tot, tlo, thi);
;                             const float bs = carry[g] * (h == 0 ? thi : 1.f);
;                             carry[g] *= tlo * thi;
; #pragma unroll
;                             for (int i = 0; i < 16; ++i) a[i] *= bs;
;                             bf16x8 pf[2];
; #pragma unroll
;                             for (int s2 = 0; s2 < 2; ++s2) {
;                                 u32x4 w; w.x = pk2(a[8 * s2 + 0], a[8 * s2 + 1]); w.y = pk2(a[8 * s2 + 2], a[8 * s2 + 3]); w.z = pk2(a[8 * s2 + 4], a[8 * s2 + 5]); w.w = pk2(a[8 * s2 + 6], a[8 * s2 + 7]);
;                                 pf[s2] = __builtin_bit_cast(bf16x8, w);
;                             }
; #pragma unroll
;                             for (int s2 = 0; s2 < 2; ++s2) { o0[g] = MFMA32(vf[s2], pf[s2], o0[g]); o1[g] = MFMA32(vf[2 + s2], pf[s2], o1[g]); }
.Lsb_lean_4:
	v_min_f32_e32 v197, 0x42ac0000, v33
	v_exp_f32_e32 v197, v197
	v_min_f32_e32 v1, 0x42ac0000, v32
	v_exp_f32_e32 v2, v1
	v_add_f32_e32 v1, 1.0, v197
	v_rcp_f32_e32 v1, v1
	v_add_f32_e32 v3, 1.0, v2
	v_rcp_f32_e32 v3, v3
	v_mul_f32_e32 v197, v197, v1
	v_mul_f32_e32 v198, v2, v3
	v_min_f32_e32 v2, 0x42ac0000, v31
	v_exp_f32_e32 v2, v2
	s_nop 0
	v_add_f32_e32 v5, 1.0, v2
	v_mul_f32_e32 v0, v3, v197
	v_mul_f32_e32 v3, v197, v198
	v_rcp_f32_e32 v5, v5
	v_min_f32_e32 v4, 0x42ac0000, v30
	v_exp_f32_e32 v4, v4
	v_mul_f32_e32 v2, v2, v5
	v_add_f32_e32 v199, 1.0, v4
	v_rcp_f32_e32 v199, v199
	v_mul_f32_e32 v7, v5, v3
	v_mul_f32_e32 v2, v2, v3
	v_mul_f32_e32 v3, v4, v199
	v_min_f32_e32 v4, 0x42ac0000, v29
	v_exp_f32_e32 v4, v4
	s_nop 0
	v_add_f32_e32 v200, 1.0, v4
	v_rcp_f32_e32 v200, v200
	v_mul_f32_e32 v8, v199, v2
	v_mul_f32_e32 v2, v3, v2
	v_mul_f32_e32 v3, v4, v200
	v_min_f32_e32 v4, 0x42ac0000, v28
	v_exp_f32_e32 v4, v4
	s_nop 0
	v_add_f32_e32 v201, 1.0, v4
	v_rcp_f32_e32 v201, v201
	v_mul_f32_e32 v9, v200, v2
	v_mul_f32_e32 v2, v3, v2
	v_mul_f32_e32 v3, v4, v201
	v_min_f32_e32 v4, 0x42ac0000, v27
	v_exp_f32_e32 v4, v4
	s_nop 0
	v_add_f32_e32 v202, 1.0, v4
	v_mul_f32_e32 v10, v201, v2
	v_rcp_f32_e32 v202, v202
	v_min_f32_e32 v5, 0x42ac0000, v26
	v_exp_f32_e32 v5, v5
	v_mul_f32_e32 v2, v3, v2
	v_mul_f32_e32 v3, v4, v202
	v_add_f32_e32 v6, 1.0, v5
	v_rcp_f32_e32 v11, v6
	v_min_f32_e32 v6, 0x42ac0000, v25
	v_exp_f32_e32 v6, v6
	v_mul_f32_e32 v12, v202, v2
	v_mul_f32_e32 v13, v3, v2
	v_mul_f32_e32 v2, v5, v11
	v_add_f32_e32 v3, 1.0, v6
	v_rcp_f32_e32 v3, v3
	v_min_f32_e32 v5, 0x42ac0000, v24
	v_exp_f32_e32 v5, v5
	v_mul_f32_e32 v4, v6, v3
	v_add_f32_e32 v6, 1.0, v5
	v_rcp_f32_e32 v6, v6
	v_mul_f32_e32 v2, v2, v13
	v_mul_f32_e32 v3, v3, v2
	v_mul_f32_e32 v2, v4, v2
	v_mul_f32_e32 v4, v5, v6
	v_min_f32_e32 v5, 0x42ac0000, v23
	v_exp_f32_e32 v5, v5
	s_nop 0
	v_add_f32_e32 v203, 1.0, v5
	v_rcp_f32_e32 v203, v203
	v_mul_f32_e32 v15, v6, v2
	v_mul_f32_e32 v2, v4, v2
	v_mul_f32_e32 v4, v5, v203
	v_min_f32_e32 v5, 0x42ac0000, v22
	v_exp_f32_e32 v5, v5
	s_nop 0
	v_add_f32_e32 v204, 1.0, v5
	v_rcp_f32_e32 v204, v204
	v_mul_f32_e32 v17, v203, v2
	v_mul_f32_e32 v2, v4, v2
	v_mul_f32_e32 v4, v5, v204
	v_min_f32_e32 v5, 0x42ac0000, v21
	v_exp_f32_e32 v5, v5
	s_nop 0
	v_add_f32_e32 v205, 1.0, v5
	v_rcp_f32_e32 v205, v205
	v_mul_f32_e32 v21, v204, v2
	v_mul_f32_e32 v2, v4, v2
	v_mul_f32_e32 v4, v5, v205
	v_min_f32_e32 v5, 0x42ac0000, v20
	v_exp_f32_e32 v5, v5
	s_nop 0
	v_add_f32_e32 v206, 1.0, v5
	v_rcp_f32_e32 v206, v206
	v_mul_f32_e32 v20, v205, v2
	v_mul_f32_e32 v2, v4, v2
	v_mul_f32_e32 v4, v5, v206
	v_min_f32_e32 v5, 0x42ac0000, v19
	v_exp_f32_e32 v5, v5
	s_nop 0
	v_add_f32_e32 v207, 1.0, v5
	v_rcp_f32_e32 v207, v207
	v_mul_f32_e32 v19, v206, v2
	v_mul_f32_e32 v2, v4, v2
	v_mul_f32_e32 v4, v5, v207
	v_min_f32_e32 v5, 0x42ac0000, v18
	v_exp_f32_e32 v5, v5
	s_nop 0
	v_add_f32_e32 v208, 1.0, v5
	v_rcp_f32_e32 v208, v208
	v_mul_f32_e32 v18, v207, v2
	v_mul_f32_e32 v2, v4, v2
	v_mul_f32_e32 v4, v5, v208
	v_mul_f32_e32 v14, v4, v2
	v_mov_b32_e32 v22, v14
	s_nop 1
	s_nop 0
	v_permlane32_swap_b32_e32 v14, v22
	v_mul_f32_e32 v5, v208, v2
	v_cndmask_b32_e64 v2, 1.0, v22, s[10:11]
	v_mul_f32_e32 v6, v190, v2
	v_mul_f32_e32 v2, v5, v6
	v_mul_f32_e32 v4, v18, v6
	v_mul_f32_e32 v5, v19, v6
	v_mul_f32_e32 v18, v20, v6
	v_mul_f32_e32 v19, v21, v6
	v_mul_f32_e32 v17, v17, v6
	v_mul_f32_e32 v15, v15, v6
	v_mul_f32_e32 v20, v3, v6
	v_cvt_pk_bf16_f32 v2, v2, v4
	v_cvt_pk_bf16_f32 v3, v5, v18
	v_cvt_pk_bf16_f32 v4, v19, v17
	v_cvt_pk_bf16_f32 v5, v15, v20
	v_cndmask_b32_e64 v15, 0, v11, s[28:29]
	s_waitcnt lgkmcnt(0)
	v_mfma_f32_32x32x16_bf16 v[66:81], v[158:161], v[2:5], v[66:81]
	v_mul_f32_e32 v11, v11, v13
	v_mul_f32_e32 v11, v11, v6
	v_mul_f32_e32 v12, v12, v6
	v_mul_f32_e32 v10, v10, v6
	v_mul_f32_e32 v9, v9, v6
	v_mfma_f32_32x32x16_bf16 v[50:65], v[154:157], v[2:5], v[50:65]
	v_mul_f32_e32 v2, v8, v6
	v_mul_f32_e32 v3, v7, v6
	v_mul_f32_e64 v4, v0, v6
	v_mul_f32_e64 v5, v1, v6
	v_cvt_pk_bf16_f32 v0, v11, v12
	v_cvt_pk_bf16_f32 v1, v10, v9
	v_cvt_pk_bf16_f32 v2, v2, v3
	v_cvt_pk_bf16_f32 v3, v4, v5
	v_mul_f32_e32 v4, v14, v22
	v_mul_f32_e32 v190, v190, v4
	v_mfma_f32_32x32x16_bf16 v[66:81], v[150:153], v[0:3], v[66:81]
